# static trailing-half priority kept through the P3/P4 epilogues (reset moved from epilogue start to epilogue end)
# baseline (speedup 1.0000x reference)
; #define PG8_BAR __builtin_amdgcn_s_barrier()
; template <class Epi, class Sched, bool ALIGN_EPI = false, bool SP2 = false>
; __device__ __forceinline__ void gemm_phase(PG8_LAS unsigned char* lds, const Gemm g, const Sched& S, const Epi& E) {
;     ...
;         if constexpr (ALIGN_EPI) { if (wr == 0) PG8_BAR; }
;         if constexpr (!Epi::AFTER_DRAIN) { E(acc, cur, wr, wc, fr, fq); S.done(cur); }
;         if (!has_next) break;
; #pragma unroll
;         for (int a = 0; a < 2; ++a)
; #pragma unroll
;             for (int b = 0; b < 2; ++b)
; #pragma unroll
;                 for (int m = 0; m < 4; ++m)
; #pragma unroll
;                     for (int n = 0; n < 2; ++n) acc[a][b][m][n] = (f32x4){0.f, 0.f, 0.f, 0.f};
;         cur = nxt; cA = nA; cB = nB; ++ui;
;         if constexpr (ALIGN_EPI) { if (wr == 1) PG8_BAR; }
.LBB0_1078:
	s_or_b64 exec, exec, s[24:25]
	s_andn2_b64 vcc, exec, s[40:41]
	s_mov_b64 s[24:25], -1
	s_setprio 0
	s_cbranch_vccnz .LBB0_1051
	s_andn2_b64 vcc, exec, s[0:1]
	s_cbranch_vccnz .LBB0_1050
	s_setprio 1
	s_barrier
	s_branch .LBB0_1050

; __device__ __forceinline__ unsigned cvt_pk_bf16(float lo, float hi) { unsigned r; asm volatile("v_cvt_pk_bf16_f32 %0, %1, %2" : "=v"(r) : "v"(lo), "v"(hi)); return r; }
;     __device__ __forceinline__ void operator()(const f32x4 (&acc)[2][2][4][2], const Unit& u, int wr, int wc, int fr, int fq) const {
;         const int row0 = u.pm * BM + wr * 64 + fr, col0 = u.pn * BM + wc * 32 + 8 * fq;
; #pragma unroll
;         for (int ai = 0; ai < 2; ++ai)
; #pragma unroll
;             for (int m = 0; m < 4; ++m) {
;                 const int row = row0 + ai * HALF + m * 16;
;                 const f32x4* sp = (const f32x4*)(ss + (size_t)row * 16);
;                 const f32x4 a0 = sp[0], a1 = sp[1], a2 = sp[2], a3 = sp[3];
;                 const float tot = ((a0.x + a0.y) + (a0.z + a0.w)) + ((a1.x + a1.y) + (a1.z + a1.w)) + ((a2.x + a2.y) + (a2.z + a2.w)) + ((a3.x + a3.y) + (a3.z + a3.w));
;                 const float rs = rsqrtf(tot * (1.0f / 1024.0f) + 1e-6f);
;                 bf16_t* rowp = O + (size_t)row * ldc + col0;
; #pragma unroll
;                 for (int bj = 0; bj < 2; ++bj) {
;                     f32x4 v0 = acc[ai][bj][m][0] * rs, v1 = acc[ai][bj][m][1] * rs;
;                     if (ACT == 1) {
; #pragma unroll
;                         for (int e = 0; e < 4; ++e) { float a = fmaxf(v0[e], 0.f); v0[e] = a * a; float b = fmaxf(v1[e], 0.f); v1[e] = b * b; }
;                     }
;                     u32x4 w; w.x = cvt_pk_bf16(v0[0], v0[1]); w.y = cvt_pk_bf16(v0[2], v0[3]); w.z = cvt_pk_bf16(v1[0], v1[1]); w.w = cvt_pk_bf16(v1[2], v1[3]);
;                     *(u32x4*)(rowp + bj * HALF) = w;
.LBB0_1155:
	v_lshl_add_u32 v152, s88, 8, v154
	v_ashrrev_i32_e32 v153, 31, v152
	v_lshlrev_b64 v[176:177], 6, v[152:153]
	v_and_or_b32 v176, v204, 48, v176
	v_lshl_add_u64 v[176:177], s[90:91], 0, v[176:177]
	v_mov_b32_e32 v178, 0x2000
	v_mov_b32_e32 v179, 0
	v_lshl_add_u64 v[178:179], v[176:177], 0, v[178:179]
	global_load_dwordx4 v[196:199], v[178:179], off
	global_load_dwordx4 v[208:211], v[178:179], off offset:1024
	global_load_dwordx4 v[212:215], v[178:179], off offset:2048
	global_load_dwordx4 v[216:219], v[178:179], off offset:3072
	v_bfe_u32 v228, v204, 2, 4
	v_and_b32_e32 v229, -16, v154
	v_or_b32_e32 v229, v229, v228
	v_lshl_add_u32 v152, s88, 8, v229
	v_ashrrev_i32_e32 v153, 31, v152
	v_and_b32_e32 v229, 3, v204
	v_lshlrev_b32_e32 v230, 3, v229
	v_and_b32_e32 v231, -32, v156
	v_or_b32_e32 v230, v230, v231
	v_lshl_add_u32 v228, v229, 4, v228
	v_lshlrev_b32_e32 v228, 2, v228
	v_lshl_or_b32 v150, s30, 8, v230
	v_ashrrev_i32_e32 v151, 31, v150
	v_lshlrev_b64 v[150:151], 1, v[150:151]
	s_mov_b64 s[24:25], -1
	v_lshlrev_b64 v[160:161], 13, v[152:153]
	v_lshl_add_u64 v[160:161], s[78:79], 0, v[160:161]
	v_lshl_add_u64 v[160:161], v[160:161], 0, v[150:151]
	s_waitcnt vmcnt(10)
	v_mov_b32_e32 v180, v232
	v_mov_b32_e32 v181, v233
	v_mov_b32_e32 v182, v234
	v_mov_b32_e32 v183, v235
	v_mov_b32_e32 v184, v236
	v_mov_b32_e32 v185, v237
	v_mov_b32_e32 v186, v238
	v_mov_b32_e32 v187, v239
	v_mov_b32_e32 v188, v240
	v_mov_b32_e32 v189, v241
	v_mov_b32_e32 v190, v242
	v_mov_b32_e32 v191, v243
	v_mov_b32_e32 v192, v244
	v_mov_b32_e32 v193, v245
	v_mov_b32_e32 v194, v246
	v_mov_b32_e32 v195, v247
	v_add_f32_e32 v180, v180, v181
	v_add_f32_e32 v182, v182, v183
	v_add_f32_e32 v184, v184, v185
	v_add_f32_e32 v186, v186, v187
	v_add_f32_e32 v188, v188, v189
	v_add_f32_e32 v190, v190, v191
	v_add_f32_e32 v192, v192, v193
	v_add_f32_e32 v194, v194, v195
	v_add_f32_e32 v180, v180, v182
	v_add_f32_e32 v184, v184, v186
	v_add_f32_e32 v188, v188, v190
	v_add_f32_e32 v192, v192, v194
	v_mov_b32_e32 v181, v180
	v_mov_b32_e32 v185, v184
	v_mov_b32_e32 v189, v188
	v_mov_b32_e32 v193, v192
	s_nop 1
	v_permlane16_swap_b32_e32 v180, v181
	v_permlane16_swap_b32_e32 v184, v185
	v_permlane16_swap_b32_e32 v188, v189
	v_permlane16_swap_b32_e32 v192, v193
	v_add_f32_e32 v180, v180, v181
	v_add_f32_e32 v184, v184, v185
	v_add_f32_e32 v188, v188, v189
	v_add_f32_e32 v192, v192, v193
	v_mov_b32_e32 v181, v180
	v_mov_b32_e32 v185, v184
	v_mov_b32_e32 v189, v188
	v_mov_b32_e32 v193, v192
	s_nop 1
	v_permlane32_swap_b32_e32 v180, v181
	v_permlane32_swap_b32_e32 v184, v185
	v_permlane32_swap_b32_e32 v188, v189
	v_permlane32_swap_b32_e32 v192, v193
	v_add_f32_e32 v180, v180, v181
	v_add_f32_e32 v184, v184, v185
	v_add_f32_e32 v188, v188, v189
	v_add_f32_e32 v192, v192, v193
	v_fmamk_f32 v180, v180, 0x3a800000, v137
	v_cmp_gt_f32_e32 vcc, s4, v180
	v_mul_f32_e32 v181, 0x4b800000, v180
	s_nop 0
	v_cndmask_b32_e32 v180, v180, v181, vcc
	v_rsq_f32_e32 v180, v180
	s_nop 0
	v_mul_f32_e32 v181, 0x45800000, v180
	v_cndmask_b32_e32 v180, v180, v181, vcc
	v_fmamk_f32 v184, v184, 0x3a800000, v137
	v_cmp_gt_f32_e32 vcc, s4, v184
	v_mul_f32_e32 v185, 0x4b800000, v184
	s_nop 0
	v_cndmask_b32_e32 v184, v184, v185, vcc
	v_rsq_f32_e32 v184, v184
	s_nop 0
	v_mul_f32_e32 v185, 0x45800000, v184
	v_cndmask_b32_e32 v184, v184, v185, vcc
	v_fmamk_f32 v188, v188, 0x3a800000, v137
	v_cmp_gt_f32_e32 vcc, s4, v188
	v_mul_f32_e32 v189, 0x4b800000, v188
	s_nop 0
	v_cndmask_b32_e32 v188, v188, v189, vcc
	v_rsq_f32_e32 v188, v188
	s_nop 0
	v_mul_f32_e32 v189, 0x45800000, v188
	v_cndmask_b32_e32 v188, v188, v189, vcc
	v_fmamk_f32 v192, v192, 0x3a800000, v137
	v_cmp_gt_f32_e32 vcc, s4, v192
	v_mul_f32_e32 v193, 0x4b800000, v192
	s_nop 0
	v_cndmask_b32_e32 v192, v192, v193, vcc
	v_rsq_f32_e32 v192, v192
	s_nop 0
	v_mul_f32_e32 v193, 0x45800000, v192
	v_cndmask_b32_e32 v192, v192, v193, vcc
	v_mov_b32_e32 v158, v180
	v_pk_mul_f32 v[120:121], v[120:121], v[158:159] op_sel_hi:[1,0]
	v_pk_mul_f32 v[124:125], v[124:125], v[158:159] op_sel_hi:[1,0]
	v_pk_mul_f32 v[122:123], v[122:123], v[158:159] op_sel_hi:[1,0]
	v_max_f32_e32 v120, 0, v120
	v_pk_mul_f32 v[126:127], v[126:127], v[158:159] op_sel_hi:[1,0]
	v_mul_f32_e32 v153, v120, v120
	v_max_f32_e32 v120, 0, v125
	v_max_f32_e32 v121, 0, v121
	v_max_f32_e32 v122, 0, v122
	v_max_f32_e32 v124, 0, v124
	v_mul_f32_e32 v120, v120, v120
	v_mul_f32_e32 v125, v121, v121
	v_max_f32_e32 v121, 0, v126
	v_mul_f32_e32 v126, v122, v122
	v_max_f32_e32 v122, 0, v127
	v_max_f32_e32 v123, 0, v123
	v_pk_mul_f32 v[112:113], v[112:113], v[158:159] op_sel_hi:[1,0]
	v_mul_f32_e32 v124, v124, v124
	v_mul_f32_e32 v121, v121, v121
	v_mul_f32_e32 v122, v122, v122
	v_mul_f32_e32 v123, v123, v123
	v_cvt_pk_bf16_f32 v120, v124, v120
	v_pk_mul_f32 v[116:117], v[116:117], v[158:159] op_sel_hi:[1,0]
	v_pk_mul_f32 v[114:115], v[114:115], v[158:159] op_sel_hi:[1,0]
	v_max_f32_e32 v112, 0, v112
	v_cvt_pk_bf16_f32 v121, v121, v122
	v_cvt_pk_bf16_f32 v122, v153, v125
	v_cvt_pk_bf16_f32 v123, v126, v123
	ds_bpermute_b32 v220, v228, v120
	ds_bpermute_b32 v221, v228, v121
	ds_bpermute_b32 v222, v228, v122
	ds_bpermute_b32 v223, v228, v123
	v_pk_mul_f32 v[118:119], v[118:119], v[158:159] op_sel_hi:[1,0]
	v_max_f32_e32 v113, 0, v113
	v_mul_f32_e32 v120, v112, v112
	v_max_f32_e32 v112, 0, v117
	v_max_f32_e32 v114, 0, v114
	v_max_f32_e32 v116, 0, v116
	v_mul_f32_e32 v112, v112, v112
	v_mul_f32_e32 v117, v113, v113
	v_max_f32_e32 v113, 0, v118
	v_mul_f32_e32 v118, v114, v114
	v_max_f32_e32 v114, 0, v119
	v_max_f32_e32 v115, 0, v115
	v_mul_f32_e32 v116, v116, v116
	v_mul_f32_e32 v113, v113, v113
	v_mul_f32_e32 v114, v114, v114
	v_mul_f32_e32 v115, v115, v115
	v_cvt_pk_bf16_f32 v112, v116, v112
	v_cvt_pk_bf16_f32 v113, v113, v114
	v_cvt_pk_bf16_f32 v114, v120, v117
	v_cvt_pk_bf16_f32 v115, v118, v115
	ds_bpermute_b32 v224, v228, v112
	ds_bpermute_b32 v225, v228, v113
	ds_bpermute_b32 v226, v228, v114
	ds_bpermute_b32 v227, v228, v115
	s_waitcnt lgkmcnt(4)
; __device__ __forceinline__ unsigned cvt_pk_bf16(float lo, float hi) { unsigned r; asm volatile("v_cvt_pk_bf16_f32 %0, %1, %2" : "=v"(r) : "v"(lo), "v"(hi)); return r; }
;     __device__ __forceinline__ void operator()(const f32x4 (&acc)[2][2][4][2], const Unit& u, int wr, int wc, int fr, int fq) const {
;     ...
;                 const int row = row0 + ai * HALF + m * 16;
;                 const f32x4* sp = (const f32x4*)(ss + (size_t)row * 16);
;                 const f32x4 a0 = sp[0], a1 = sp[1], a2 = sp[2], a3 = sp[3];
;                 const float tot = ((a0.x + a0.y) + (a0.z + a0.w)) + ((a1.x + a1.y) + (a1.z + a1.w)) + ((a2.x + a2.y) + (a2.z + a2.w)) + ((a3.x + a3.y) + (a3.z + a3.w));
;                 const float rs = rsqrtf(tot * (1.0f / 1024.0f) + 1e-6f);
;                 bf16_t* rowp = O + (size_t)row * ldc + col0;
; #pragma unroll
;                 for (int bj = 0; bj < 2; ++bj) {
;                     f32x4 v0 = acc[ai][bj][m][0] * rs, v1 = acc[ai][bj][m][1] * rs;
;                     if (ACT == 1) {
; #pragma unroll
;                         for (int e = 0; e < 4; ++e) { float a = fmaxf(v0[e], 0.f); v0[e] = a * a; float b = fmaxf(v1[e], 0.f); v1[e] = b * b; }
;                     }
;                     u32x4 w; w.x = cvt_pk_bf16(v0[0], v0[1]); w.y = cvt_pk_bf16(v0[2], v0[3]); w.z = cvt_pk_bf16(v1[0], v1[1]); w.w = cvt_pk_bf16(v1[2], v1[3]);
;                     *(u32x4*)(rowp + bj * HALF) = w;
	global_store_dwordx4 v[160:161], v[220:223], off
	s_waitcnt lgkmcnt(0)
	global_store_dwordx4 v[160:161], v[224:227], off offset:256
	s_nop 1
	v_or_b32_e32 v112, 16, v152
	v_ashrrev_i32_e32 v113, 31, v112
	v_lshlrev_b64 v[112:113], 13, v[112:113]
	v_lshl_add_u64 v[112:113], s[78:79], 0, v[112:113]
	v_lshl_add_u64 v[112:113], v[112:113], 0, v[150:151]
	v_mov_b32_e32 v114, v184
	v_pk_mul_f32 v[104:105], v[104:105], v[114:115] op_sel_hi:[1,0]
	v_pk_mul_f32 v[108:109], v[108:109], v[114:115] op_sel_hi:[1,0]
	v_pk_mul_f32 v[106:107], v[106:107], v[114:115] op_sel_hi:[1,0]
	v_max_f32_e32 v104, 0, v104
	v_pk_mul_f32 v[110:111], v[110:111], v[114:115] op_sel_hi:[1,0]
	v_mul_f32_e32 v115, v104, v104
	v_max_f32_e32 v104, 0, v109
	v_max_f32_e32 v105, 0, v105
	v_max_f32_e32 v106, 0, v106
	v_max_f32_e32 v108, 0, v108
	v_mul_f32_e32 v104, v104, v104
	v_mul_f32_e32 v109, v105, v105
	v_max_f32_e32 v105, 0, v110
	v_mul_f32_e32 v110, v106, v106
	v_max_f32_e32 v106, 0, v111
	v_max_f32_e32 v107, 0, v107
	v_pk_mul_f32 v[96:97], v[96:97], v[114:115] op_sel_hi:[1,0]
	v_mul_f32_e32 v108, v108, v108
	v_mul_f32_e32 v105, v105, v105
	v_mul_f32_e32 v106, v106, v106
	v_mul_f32_e32 v107, v107, v107
	v_cvt_pk_bf16_f32 v104, v108, v104
	v_pk_mul_f32 v[100:101], v[100:101], v[114:115] op_sel_hi:[1,0]
	v_pk_mul_f32 v[98:99], v[98:99], v[114:115] op_sel_hi:[1,0]
	v_max_f32_e32 v96, 0, v96
	v_cvt_pk_bf16_f32 v105, v105, v106
	v_cvt_pk_bf16_f32 v106, v115, v109
	v_cvt_pk_bf16_f32 v107, v110, v107
	ds_bpermute_b32 v220, v228, v104
	ds_bpermute_b32 v221, v228, v105
	ds_bpermute_b32 v222, v228, v106
	ds_bpermute_b32 v223, v228, v107
	v_pk_mul_f32 v[102:103], v[102:103], v[114:115] op_sel_hi:[1,0]
	v_max_f32_e32 v97, 0, v97
	v_mul_f32_e32 v104, v96, v96
	v_max_f32_e32 v96, 0, v101
	v_max_f32_e32 v98, 0, v98
	v_max_f32_e32 v100, 0, v100
	v_mul_f32_e32 v96, v96, v96
	v_mul_f32_e32 v101, v97, v97
	v_max_f32_e32 v97, 0, v102
	v_mul_f32_e32 v102, v98, v98
	v_max_f32_e32 v98, 0, v103
	v_max_f32_e32 v99, 0, v99
	v_mul_f32_e32 v100, v100, v100
	v_mul_f32_e32 v97, v97, v97
	v_mul_f32_e32 v98, v98, v98
	v_mul_f32_e32 v99, v99, v99
	v_cvt_pk_bf16_f32 v96, v100, v96
	v_cvt_pk_bf16_f32 v97, v97, v98
	v_cvt_pk_bf16_f32 v98, v104, v101
	v_cvt_pk_bf16_f32 v99, v102, v99
	ds_bpermute_b32 v224, v228, v96
	ds_bpermute_b32 v225, v228, v97
	ds_bpermute_b32 v226, v228, v98
	ds_bpermute_b32 v227, v228, v99
	s_waitcnt lgkmcnt(4)
	global_store_dwordx4 v[112:113], v[220:223], off
	s_waitcnt lgkmcnt(0)
	global_store_dwordx4 v[112:113], v[224:227], off offset:256
	s_nop 1
	v_or_b32_e32 v96, 32, v152
	v_ashrrev_i32_e32 v97, 31, v96
	v_lshlrev_b64 v[96:97], 13, v[96:97]
	v_lshl_add_u64 v[96:97], s[78:79], 0, v[96:97]
	v_lshl_add_u64 v[96:97], v[96:97], 0, v[150:151]
	v_mov_b32_e32 v98, v188
	v_pk_mul_f32 v[88:89], v[88:89], v[98:99] op_sel_hi:[1,0]
	v_pk_mul_f32 v[92:93], v[92:93], v[98:99] op_sel_hi:[1,0]
	v_pk_mul_f32 v[90:91], v[90:91], v[98:99] op_sel_hi:[1,0]
	v_max_f32_e32 v88, 0, v88
	v_pk_mul_f32 v[94:95], v[94:95], v[98:99] op_sel_hi:[1,0]
	v_mul_f32_e32 v99, v88, v88
	v_max_f32_e32 v88, 0, v93
	v_max_f32_e32 v89, 0, v89
	v_max_f32_e32 v90, 0, v90
	v_max_f32_e32 v92, 0, v92
	v_mul_f32_e32 v88, v88, v88
	v_mul_f32_e32 v93, v89, v89
	v_max_f32_e32 v89, 0, v94
	v_mul_f32_e32 v94, v90, v90
	v_max_f32_e32 v90, 0, v95
	v_max_f32_e32 v91, 0, v91
	v_pk_mul_f32 v[80:81], v[80:81], v[98:99] op_sel_hi:[1,0]
	v_mul_f32_e32 v92, v92, v92
	v_mul_f32_e32 v89, v89, v89
	v_mul_f32_e32 v90, v90, v90
	v_mul_f32_e32 v91, v91, v91
	v_cvt_pk_bf16_f32 v88, v92, v88
	v_pk_mul_f32 v[84:85], v[84:85], v[98:99] op_sel_hi:[1,0]
	v_pk_mul_f32 v[82:83], v[82:83], v[98:99] op_sel_hi:[1,0]
	v_max_f32_e32 v80, 0, v80
	v_cvt_pk_bf16_f32 v89, v89, v90
	v_cvt_pk_bf16_f32 v90, v99, v93
	v_cvt_pk_bf16_f32 v91, v94, v91
	ds_bpermute_b32 v220, v228, v88
	ds_bpermute_b32 v221, v228, v89
	ds_bpermute_b32 v222, v228, v90
	ds_bpermute_b32 v223, v228, v91
	v_pk_mul_f32 v[86:87], v[86:87], v[98:99] op_sel_hi:[1,0]
	v_max_f32_e32 v81, 0, v81
	v_mul_f32_e32 v88, v80, v80
	v_max_f32_e32 v80, 0, v85
	v_max_f32_e32 v82, 0, v82
	v_max_f32_e32 v84, 0, v84
	v_mul_f32_e32 v80, v80, v80
	v_mul_f32_e32 v85, v81, v81
	v_max_f32_e32 v81, 0, v86
	v_mul_f32_e32 v86, v82, v82
	v_max_f32_e32 v82, 0, v87
	v_max_f32_e32 v83, 0, v83
	v_mul_f32_e32 v84, v84, v84
	v_mul_f32_e32 v81, v81, v81
	v_mul_f32_e32 v82, v82, v82
	v_mul_f32_e32 v83, v83, v83
	v_cvt_pk_bf16_f32 v80, v84, v80
	v_cvt_pk_bf16_f32 v81, v81, v82
	v_cvt_pk_bf16_f32 v82, v88, v85
	v_cvt_pk_bf16_f32 v83, v86, v83
	ds_bpermute_b32 v224, v228, v80
	ds_bpermute_b32 v225, v228, v81
	ds_bpermute_b32 v226, v228, v82
	ds_bpermute_b32 v227, v228, v83
	s_waitcnt lgkmcnt(4)
	global_store_dwordx4 v[96:97], v[220:223], off
	s_waitcnt lgkmcnt(0)
; __device__ __forceinline__ unsigned cvt_pk_bf16(float lo, float hi) { unsigned r; asm volatile("v_cvt_pk_bf16_f32 %0, %1, %2" : "=v"(r) : "v"(lo), "v"(hi)); return r; }
;     __device__ __forceinline__ void operator()(const f32x4 (&acc)[2][2][4][2], const Unit& u, int wr, int wc, int fr, int fq) const {
;     ...
;                 const int row = row0 + ai * HALF + m * 16;
;                 const f32x4* sp = (const f32x4*)(ss + (size_t)row * 16);
;                 const f32x4 a0 = sp[0], a1 = sp[1], a2 = sp[2], a3 = sp[3];
;                 const float tot = ((a0.x + a0.y) + (a0.z + a0.w)) + ((a1.x + a1.y) + (a1.z + a1.w)) + ((a2.x + a2.y) + (a2.z + a2.w)) + ((a3.x + a3.y) + (a3.z + a3.w));
;                 const float rs = rsqrtf(tot * (1.0f / 1024.0f) + 1e-6f);
;                 bf16_t* rowp = O + (size_t)row * ldc + col0;
; #pragma unroll
;                 for (int bj = 0; bj < 2; ++bj) {
;                     f32x4 v0 = acc[ai][bj][m][0] * rs, v1 = acc[ai][bj][m][1] * rs;
;                     if (ACT == 1) {
; #pragma unroll
;                         for (int e = 0; e < 4; ++e) { float a = fmaxf(v0[e], 0.f); v0[e] = a * a; float b = fmaxf(v1[e], 0.f); v1[e] = b * b; }
;                     }
;                     u32x4 w; w.x = cvt_pk_bf16(v0[0], v0[1]); w.y = cvt_pk_bf16(v0[2], v0[3]); w.z = cvt_pk_bf16(v1[0], v1[1]); w.w = cvt_pk_bf16(v1[2], v1[3]);
;                     *(u32x4*)(rowp + bj * HALF) = w;
	global_store_dwordx4 v[96:97], v[224:227], off offset:256
	s_nop 1
	v_or_b32_e32 v80, 48, v152
	v_ashrrev_i32_e32 v81, 31, v80
	v_lshlrev_b64 v[80:81], 13, v[80:81]
	v_lshl_add_u64 v[80:81], s[78:79], 0, v[80:81]
	v_lshl_add_u64 v[80:81], v[80:81], 0, v[150:151]
	v_mov_b32_e32 v82, v192
	v_pk_mul_f32 v[72:73], v[72:73], v[82:83] op_sel_hi:[1,0]
	v_pk_mul_f32 v[76:77], v[76:77], v[82:83] op_sel_hi:[1,0]
	v_pk_mul_f32 v[74:75], v[74:75], v[82:83] op_sel_hi:[1,0]
	v_max_f32_e32 v72, 0, v72
	v_pk_mul_f32 v[78:79], v[78:79], v[82:83] op_sel_hi:[1,0]
	v_mul_f32_e32 v83, v72, v72
	v_max_f32_e32 v72, 0, v77
	v_max_f32_e32 v73, 0, v73
	v_max_f32_e32 v74, 0, v74
	v_max_f32_e32 v76, 0, v76
	v_mul_f32_e32 v72, v72, v72
	v_mul_f32_e32 v77, v73, v73
	v_max_f32_e32 v73, 0, v78
	v_mul_f32_e32 v78, v74, v74
	v_max_f32_e32 v74, 0, v79
	v_max_f32_e32 v75, 0, v75
	v_pk_mul_f32 v[64:65], v[64:65], v[82:83] op_sel_hi:[1,0]
	v_mul_f32_e32 v76, v76, v76
	v_mul_f32_e32 v73, v73, v73
	v_mul_f32_e32 v74, v74, v74
	v_mul_f32_e32 v75, v75, v75
	v_cvt_pk_bf16_f32 v72, v76, v72
	v_pk_mul_f32 v[68:69], v[68:69], v[82:83] op_sel_hi:[1,0]
	v_pk_mul_f32 v[66:67], v[66:67], v[82:83] op_sel_hi:[1,0]
	v_max_f32_e32 v64, 0, v64
	v_cvt_pk_bf16_f32 v73, v73, v74
	v_cvt_pk_bf16_f32 v74, v83, v77
	v_cvt_pk_bf16_f32 v75, v78, v75
	ds_bpermute_b32 v220, v228, v72
	ds_bpermute_b32 v221, v228, v73
	ds_bpermute_b32 v222, v228, v74
	ds_bpermute_b32 v223, v228, v75
	v_pk_mul_f32 v[70:71], v[70:71], v[82:83] op_sel_hi:[1,0]
	v_max_f32_e32 v65, 0, v65
	v_mul_f32_e32 v72, v64, v64
	v_max_f32_e32 v64, 0, v69
	v_max_f32_e32 v66, 0, v66
	v_max_f32_e32 v68, 0, v68
	v_mul_f32_e32 v64, v64, v64
	v_mul_f32_e32 v69, v65, v65
	v_max_f32_e32 v65, 0, v70
	v_mul_f32_e32 v70, v66, v66
	v_max_f32_e32 v66, 0, v71
	v_max_f32_e32 v67, 0, v67
	v_mul_f32_e32 v68, v68, v68
	v_mul_f32_e32 v65, v65, v65
	v_mul_f32_e32 v66, v66, v66
	v_mul_f32_e32 v67, v67, v67
	v_cvt_pk_bf16_f32 v64, v68, v64
	v_cvt_pk_bf16_f32 v65, v65, v66
	v_cvt_pk_bf16_f32 v66, v72, v69
	v_cvt_pk_bf16_f32 v67, v70, v67
	ds_bpermute_b32 v224, v228, v64
	ds_bpermute_b32 v225, v228, v65
	ds_bpermute_b32 v226, v228, v66
	ds_bpermute_b32 v227, v228, v67
	s_waitcnt lgkmcnt(4)
	global_store_dwordx4 v[80:81], v[220:223], off
	s_waitcnt lgkmcnt(0)
	global_store_dwordx4 v[80:81], v[224:227], off offset:256
	s_nop 1
	v_add_u32_e32 v64, 0x80, v152
	v_ashrrev_i32_e32 v65, 31, v64
	v_lshlrev_b64 v[64:65], 13, v[64:65]
	v_lshl_add_u64 v[64:65], s[78:79], 0, v[64:65]
	v_lshl_add_u64 v[64:65], v[64:65], 0, v[150:151]
	s_waitcnt vmcnt(8)
	v_add_f32_e32 v196, v196, v197
	v_add_f32_e32 v198, v198, v199
	v_add_f32_e32 v208, v208, v209
	v_add_f32_e32 v210, v210, v211
	v_add_f32_e32 v212, v212, v213
	v_add_f32_e32 v214, v214, v215
	v_add_f32_e32 v216, v216, v217
	v_add_f32_e32 v218, v218, v219
	v_add_f32_e32 v196, v196, v198
	v_add_f32_e32 v208, v208, v210
	v_add_f32_e32 v212, v212, v214
	v_add_f32_e32 v216, v216, v218
	v_mov_b32_e32 v197, v196
	v_mov_b32_e32 v209, v208
	v_mov_b32_e32 v213, v212
	v_mov_b32_e32 v217, v216
	s_nop 1
	v_permlane16_swap_b32_e32 v196, v197
	v_permlane16_swap_b32_e32 v208, v209
	v_permlane16_swap_b32_e32 v212, v213
	v_permlane16_swap_b32_e32 v216, v217
	v_add_f32_e32 v196, v196, v197
	v_add_f32_e32 v208, v208, v209
	v_add_f32_e32 v212, v212, v213
	v_add_f32_e32 v216, v216, v217
	v_mov_b32_e32 v197, v196
	v_mov_b32_e32 v209, v208
	v_mov_b32_e32 v213, v212
	v_mov_b32_e32 v217, v216
	s_nop 1
	v_permlane32_swap_b32_e32 v196, v197
	v_permlane32_swap_b32_e32 v208, v209
	v_permlane32_swap_b32_e32 v212, v213
	v_permlane32_swap_b32_e32 v216, v217
	v_add_f32_e32 v196, v196, v197
	v_add_f32_e32 v208, v208, v209
	v_add_f32_e32 v212, v212, v213
	v_add_f32_e32 v216, v216, v217
	v_fmamk_f32 v196, v196, 0x3a800000, v137
	v_cmp_gt_f32_e32 vcc, s4, v196
	v_mul_f32_e32 v197, 0x4b800000, v196
	s_nop 0
	v_cndmask_b32_e32 v196, v196, v197, vcc
	v_rsq_f32_e32 v196, v196
	s_nop 0
	v_mul_f32_e32 v197, 0x45800000, v196
	v_cndmask_b32_e32 v196, v196, v197, vcc
	v_fmamk_f32 v208, v208, 0x3a800000, v137
	v_cmp_gt_f32_e32 vcc, s4, v208
	v_mul_f32_e32 v209, 0x4b800000, v208
	s_nop 0
	v_cndmask_b32_e32 v208, v208, v209, vcc
	v_rsq_f32_e32 v208, v208
	s_nop 0
	v_mul_f32_e32 v209, 0x45800000, v208
	v_cndmask_b32_e32 v208, v208, v209, vcc
	v_fmamk_f32 v212, v212, 0x3a800000, v137
	v_cmp_gt_f32_e32 vcc, s4, v212
	v_mul_f32_e32 v213, 0x4b800000, v212
	s_nop 0
	v_cndmask_b32_e32 v212, v212, v213, vcc
	v_rsq_f32_e32 v212, v212
	s_nop 0
	v_mul_f32_e32 v213, 0x45800000, v212
	v_cndmask_b32_e32 v212, v212, v213, vcc
	v_fmamk_f32 v216, v216, 0x3a800000, v137
	v_cmp_gt_f32_e32 vcc, s4, v216
	v_mul_f32_e32 v217, 0x4b800000, v216
	s_nop 0
	v_cndmask_b32_e32 v216, v216, v217, vcc
	v_rsq_f32_e32 v216, v216
	s_nop 0
	v_mul_f32_e32 v217, 0x45800000, v216
	v_cndmask_b32_e32 v216, v216, v217, vcc
	v_mov_b32_e32 v66, v196
	v_pk_mul_f32 v[56:57], v[56:57], v[66:67] op_sel_hi:[1,0]
	v_pk_mul_f32 v[60:61], v[60:61], v[66:67] op_sel_hi:[1,0]
	v_pk_mul_f32 v[58:59], v[58:59], v[66:67] op_sel_hi:[1,0]
	v_max_f32_e32 v56, 0, v56
	v_pk_mul_f32 v[62:63], v[62:63], v[66:67] op_sel_hi:[1,0]
	v_mul_f32_e32 v67, v56, v56
	v_max_f32_e32 v56, 0, v61
	v_max_f32_e32 v57, 0, v57
	v_max_f32_e32 v58, 0, v58
	v_max_f32_e32 v60, 0, v60
	v_mul_f32_e32 v56, v56, v56
	v_mul_f32_e32 v61, v57, v57
	v_max_f32_e32 v57, 0, v62
	v_mul_f32_e32 v62, v58, v58
	v_max_f32_e32 v58, 0, v63
	v_max_f32_e32 v59, 0, v59
	v_pk_mul_f32 v[48:49], v[48:49], v[66:67] op_sel_hi:[1,0]
	v_mul_f32_e32 v60, v60, v60
	v_mul_f32_e32 v57, v57, v57
	v_mul_f32_e32 v58, v58, v58
	v_mul_f32_e32 v59, v59, v59
	v_cvt_pk_bf16_f32 v56, v60, v56
	v_pk_mul_f32 v[52:53], v[52:53], v[66:67] op_sel_hi:[1,0]
	v_pk_mul_f32 v[50:51], v[50:51], v[66:67] op_sel_hi:[1,0]
	v_max_f32_e32 v48, 0, v48
	v_cvt_pk_bf16_f32 v57, v57, v58
	v_cvt_pk_bf16_f32 v58, v67, v61
	v_cvt_pk_bf16_f32 v59, v62, v59
	ds_bpermute_b32 v220, v228, v56
	ds_bpermute_b32 v221, v228, v57
	ds_bpermute_b32 v222, v228, v58
	ds_bpermute_b32 v223, v228, v59
	v_pk_mul_f32 v[54:55], v[54:55], v[66:67] op_sel_hi:[1,0]
	v_max_f32_e32 v49, 0, v49
	v_mul_f32_e32 v56, v48, v48
	v_max_f32_e32 v48, 0, v53
	v_max_f32_e32 v50, 0, v50
	v_max_f32_e32 v52, 0, v52
	v_mul_f32_e32 v48, v48, v48
	v_mul_f32_e32 v53, v49, v49
	v_max_f32_e32 v49, 0, v54
	v_mul_f32_e32 v54, v50, v50
	v_max_f32_e32 v50, 0, v55
	v_max_f32_e32 v51, 0, v51
	v_mul_f32_e32 v52, v52, v52
	v_mul_f32_e32 v49, v49, v49
	v_mul_f32_e32 v50, v50, v50
	v_mul_f32_e32 v51, v51, v51
	v_cvt_pk_bf16_f32 v48, v52, v48
	v_cvt_pk_bf16_f32 v49, v49, v50
	v_cvt_pk_bf16_f32 v50, v56, v53
	v_cvt_pk_bf16_f32 v51, v54, v51
	ds_bpermute_b32 v224, v228, v48
	ds_bpermute_b32 v225, v228, v49
	ds_bpermute_b32 v226, v228, v50
	ds_bpermute_b32 v227, v228, v51
	s_waitcnt lgkmcnt(4)
; __device__ __forceinline__ unsigned cvt_pk_bf16(float lo, float hi) { unsigned r; asm volatile("v_cvt_pk_bf16_f32 %0, %1, %2" : "=v"(r) : "v"(lo), "v"(hi)); return r; }
; #define PG8_BAR __builtin_amdgcn_s_barrier()
;     __device__ __forceinline__ void operator()(const f32x4 (&acc)[2][2][4][2], const Unit& u, int wr, int wc, int fr, int fq) const {
;     ...
;                 const int row = row0 + ai * HALF + m * 16;
;                 const f32x4* sp = (const f32x4*)(ss + (size_t)row * 16);
;                 const f32x4 a0 = sp[0], a1 = sp[1], a2 = sp[2], a3 = sp[3];
;                 const float tot = ((a0.x + a0.y) + (a0.z + a0.w)) + ((a1.x + a1.y) + (a1.z + a1.w)) + ((a2.x + a2.y) + (a2.z + a2.w)) + ((a3.x + a3.y) + (a3.z + a3.w));
;                 const float rs = rsqrtf(tot * (1.0f / 1024.0f) + 1e-6f);
;                 bf16_t* rowp = O + (size_t)row * ldc + col0;
; #pragma unroll
;                 for (int bj = 0; bj < 2; ++bj) {
;                     f32x4 v0 = acc[ai][bj][m][0] * rs, v1 = acc[ai][bj][m][1] * rs;
;                     if (ACT == 1) {
; #pragma unroll
;                         for (int e = 0; e < 4; ++e) { float a = fmaxf(v0[e], 0.f); v0[e] = a * a; float b = fmaxf(v1[e], 0.f); v1[e] = b * b; }
;                     }
;                     u32x4 w; w.x = cvt_pk_bf16(v0[0], v0[1]); w.y = cvt_pk_bf16(v0[2], v0[3]); w.z = cvt_pk_bf16(v1[0], v1[1]); w.w = cvt_pk_bf16(v1[2], v1[3]);
;                     *(u32x4*)(rowp + bj * HALF) = w;
; template <class Epi, class Sched, bool ALIGN_EPI = false, bool SP2 = false>
; __device__ __forceinline__ void gemm_phase(PG8_LAS unsigned char* lds, const Gemm g, const Sched& S, const Epi& E) {
;     ...
;         cur = nxt; cA = nA; cB = nB; ++ui;
;         if constexpr (ALIGN_EPI) { if (wr == 1) PG8_BAR; }
	global_store_dwordx4 v[64:65], v[220:223], off
	s_waitcnt lgkmcnt(0)
	global_store_dwordx4 v[64:65], v[224:227], off offset:256
	s_nop 1
	v_add_u32_e32 v48, 0x90, v152
	v_ashrrev_i32_e32 v49, 31, v48
	v_lshlrev_b64 v[48:49], 13, v[48:49]
	v_lshl_add_u64 v[48:49], s[78:79], 0, v[48:49]
	v_lshl_add_u64 v[48:49], v[48:49], 0, v[150:151]
	v_mov_b32_e32 v50, v208
	v_pk_mul_f32 v[40:41], v[40:41], v[50:51] op_sel_hi:[1,0]
	v_pk_mul_f32 v[44:45], v[44:45], v[50:51] op_sel_hi:[1,0]
	v_pk_mul_f32 v[42:43], v[42:43], v[50:51] op_sel_hi:[1,0]
	v_max_f32_e32 v40, 0, v40
	v_pk_mul_f32 v[46:47], v[46:47], v[50:51] op_sel_hi:[1,0]
	v_mul_f32_e32 v51, v40, v40
	v_max_f32_e32 v40, 0, v45
	v_max_f32_e32 v41, 0, v41
	v_max_f32_e32 v42, 0, v42
	v_max_f32_e32 v44, 0, v44
	v_mul_f32_e32 v40, v40, v40
	v_mul_f32_e32 v45, v41, v41
	v_max_f32_e32 v41, 0, v46
	v_mul_f32_e32 v46, v42, v42
	v_max_f32_e32 v42, 0, v47
	v_max_f32_e32 v43, 0, v43
	v_pk_mul_f32 v[32:33], v[32:33], v[50:51] op_sel_hi:[1,0]
	v_mul_f32_e32 v44, v44, v44
	v_mul_f32_e32 v41, v41, v41
	v_mul_f32_e32 v42, v42, v42
	v_mul_f32_e32 v43, v43, v43
	v_cvt_pk_bf16_f32 v40, v44, v40
	v_pk_mul_f32 v[36:37], v[36:37], v[50:51] op_sel_hi:[1,0]
	v_pk_mul_f32 v[34:35], v[34:35], v[50:51] op_sel_hi:[1,0]
	v_max_f32_e32 v32, 0, v32
	v_cvt_pk_bf16_f32 v41, v41, v42
	v_cvt_pk_bf16_f32 v42, v51, v45
	v_cvt_pk_bf16_f32 v43, v46, v43
	ds_bpermute_b32 v220, v228, v40
	ds_bpermute_b32 v221, v228, v41
	ds_bpermute_b32 v222, v228, v42
	ds_bpermute_b32 v223, v228, v43
	v_pk_mul_f32 v[38:39], v[38:39], v[50:51] op_sel_hi:[1,0]
	v_max_f32_e32 v33, 0, v33
	v_mul_f32_e32 v40, v32, v32
	v_max_f32_e32 v32, 0, v37
	v_max_f32_e32 v34, 0, v34
	v_max_f32_e32 v36, 0, v36
	v_mul_f32_e32 v32, v32, v32
	v_mul_f32_e32 v37, v33, v33
	v_max_f32_e32 v33, 0, v38
	v_mul_f32_e32 v38, v34, v34
	v_max_f32_e32 v34, 0, v39
	v_max_f32_e32 v35, 0, v35
	v_mul_f32_e32 v36, v36, v36
	v_mul_f32_e32 v33, v33, v33
	v_mul_f32_e32 v34, v34, v34
	v_mul_f32_e32 v35, v35, v35
	v_cvt_pk_bf16_f32 v32, v36, v32
	v_cvt_pk_bf16_f32 v33, v33, v34
	v_cvt_pk_bf16_f32 v34, v40, v37
	v_cvt_pk_bf16_f32 v35, v38, v35
	ds_bpermute_b32 v224, v228, v32
	ds_bpermute_b32 v225, v228, v33
	ds_bpermute_b32 v226, v228, v34
	ds_bpermute_b32 v227, v228, v35
	s_waitcnt lgkmcnt(4)
	global_store_dwordx4 v[48:49], v[220:223], off
	s_waitcnt lgkmcnt(0)
	global_store_dwordx4 v[48:49], v[224:227], off offset:256
	s_nop 1
	v_add_u32_e32 v32, 0xa0, v152
	v_ashrrev_i32_e32 v33, 31, v32
	v_lshlrev_b64 v[32:33], 13, v[32:33]
	v_lshl_add_u64 v[32:33], s[78:79], 0, v[32:33]
	v_lshl_add_u64 v[32:33], v[32:33], 0, v[150:151]
	v_mov_b32_e32 v34, v212
	v_pk_mul_f32 v[24:25], v[24:25], v[34:35] op_sel_hi:[1,0]
	v_pk_mul_f32 v[28:29], v[28:29], v[34:35] op_sel_hi:[1,0]
	v_pk_mul_f32 v[26:27], v[26:27], v[34:35] op_sel_hi:[1,0]
	v_max_f32_e32 v24, 0, v24
	v_pk_mul_f32 v[30:31], v[30:31], v[34:35] op_sel_hi:[1,0]
	v_mul_f32_e32 v35, v24, v24
	v_max_f32_e32 v24, 0, v29
	v_max_f32_e32 v25, 0, v25
	v_max_f32_e32 v26, 0, v26
	v_max_f32_e32 v28, 0, v28
	v_mul_f32_e32 v24, v24, v24
	v_mul_f32_e32 v29, v25, v25
	v_max_f32_e32 v25, 0, v30
	v_mul_f32_e32 v30, v26, v26
	v_max_f32_e32 v26, 0, v31
	v_max_f32_e32 v27, 0, v27
	v_pk_mul_f32 v[16:17], v[16:17], v[34:35] op_sel_hi:[1,0]
	v_mul_f32_e32 v28, v28, v28
	v_mul_f32_e32 v25, v25, v25
	v_mul_f32_e32 v26, v26, v26
	v_mul_f32_e32 v27, v27, v27
	v_cvt_pk_bf16_f32 v24, v28, v24
	v_pk_mul_f32 v[20:21], v[20:21], v[34:35] op_sel_hi:[1,0]
	v_pk_mul_f32 v[18:19], v[18:19], v[34:35] op_sel_hi:[1,0]
	v_max_f32_e32 v16, 0, v16
	v_cvt_pk_bf16_f32 v25, v25, v26
	v_cvt_pk_bf16_f32 v26, v35, v29
	v_cvt_pk_bf16_f32 v27, v30, v27
	ds_bpermute_b32 v220, v228, v24
	ds_bpermute_b32 v221, v228, v25
	ds_bpermute_b32 v222, v228, v26
	ds_bpermute_b32 v223, v228, v27
	v_pk_mul_f32 v[22:23], v[22:23], v[34:35] op_sel_hi:[1,0]
	v_max_f32_e32 v17, 0, v17
	v_mul_f32_e32 v24, v16, v16
	v_max_f32_e32 v16, 0, v21
	v_max_f32_e32 v18, 0, v18
	v_max_f32_e32 v20, 0, v20
	v_mul_f32_e32 v16, v16, v16
	v_mul_f32_e32 v21, v17, v17
	v_max_f32_e32 v17, 0, v22
	v_mul_f32_e32 v22, v18, v18
	v_max_f32_e32 v18, 0, v23
	v_max_f32_e32 v19, 0, v19
	v_mul_f32_e32 v20, v20, v20
	v_mul_f32_e32 v17, v17, v17
	v_mul_f32_e32 v18, v18, v18
	v_mul_f32_e32 v19, v19, v19
	v_cvt_pk_bf16_f32 v16, v20, v16
	v_cvt_pk_bf16_f32 v17, v17, v18
	v_cvt_pk_bf16_f32 v18, v24, v21
	v_cvt_pk_bf16_f32 v19, v22, v19
	ds_bpermute_b32 v224, v228, v16
	ds_bpermute_b32 v225, v228, v17
	ds_bpermute_b32 v226, v228, v18
	ds_bpermute_b32 v227, v228, v19
	s_waitcnt lgkmcnt(4)
	global_store_dwordx4 v[32:33], v[220:223], off
	s_waitcnt lgkmcnt(0)
	global_store_dwordx4 v[32:33], v[224:227], off offset:256
	s_nop 1
	v_add_u32_e32 v16, 0xb0, v152
	v_ashrrev_i32_e32 v17, 31, v16
	v_lshlrev_b64 v[16:17], 13, v[16:17]
	v_lshl_add_u64 v[16:17], s[78:79], 0, v[16:17]
	v_lshl_add_u64 v[16:17], v[16:17], 0, v[150:151]
	v_mov_b32_e32 v18, v216
	v_pk_mul_f32 v[8:9], v[8:9], v[18:19] op_sel_hi:[1,0]
	v_pk_mul_f32 v[12:13], v[12:13], v[18:19] op_sel_hi:[1,0]
	v_pk_mul_f32 v[10:11], v[10:11], v[18:19] op_sel_hi:[1,0]
	v_max_f32_e32 v8, 0, v8
	v_pk_mul_f32 v[14:15], v[14:15], v[18:19] op_sel_hi:[1,0]
	v_mul_f32_e32 v19, v8, v8
	v_max_f32_e32 v8, 0, v13
	v_max_f32_e32 v9, 0, v9
	v_max_f32_e32 v10, 0, v10
	v_max_f32_e32 v12, 0, v12
	v_mul_f32_e32 v8, v8, v8
	v_mul_f32_e32 v13, v9, v9
	v_max_f32_e32 v9, 0, v14
	v_mul_f32_e32 v14, v10, v10
	v_max_f32_e32 v10, 0, v15
	v_max_f32_e32 v11, 0, v11
	v_pk_mul_f32 v[2:3], v[2:3], v[18:19] op_sel_hi:[1,0]
	v_pk_mul_f32 v[0:1], v[0:1], v[18:19] op_sel_hi:[1,0]
	v_mul_f32_e32 v12, v12, v12
	v_mul_f32_e32 v9, v9, v9
	v_mul_f32_e32 v10, v10, v10
	v_mul_f32_e32 v11, v11, v11
	v_cvt_pk_bf16_f32 v8, v12, v8
	v_pk_mul_f32 v[6:7], v[6:7], v[18:19] op_sel_hi:[1,0]
	v_pk_mul_f32 v[4:5], v[4:5], v[18:19] op_sel_hi:[1,0]
	v_max_f32_e32 v0, 0, v0
	v_max_f32_e32 v1, 0, v1
	v_max_f32_e32 v2, 0, v2
	v_cvt_pk_bf16_f32 v9, v9, v10
	v_cvt_pk_bf16_f32 v10, v19, v13
	v_cvt_pk_bf16_f32 v11, v14, v11
	ds_bpermute_b32 v220, v228, v8
	ds_bpermute_b32 v221, v228, v9
	ds_bpermute_b32 v222, v228, v10
	ds_bpermute_b32 v223, v228, v11
	v_max_f32_e32 v3, 0, v3
	v_max_f32_e32 v4, 0, v4
	v_mul_f32_e32 v8, v0, v0
	v_max_f32_e32 v0, 0, v5
	v_mul_f32_e32 v5, v1, v1
	v_max_f32_e32 v1, 0, v6
	v_mul_f32_e32 v6, v2, v2
	v_max_f32_e32 v2, 0, v7
	v_mul_f32_e32 v0, v0, v0
	v_mul_f32_e32 v1, v1, v1
	v_mul_f32_e32 v2, v2, v2
	v_mul_f32_e32 v3, v3, v3
	s_andn2_b64 vcc, exec, s[38:39]
	v_mul_f32_e32 v4, v4, v4
	v_cvt_pk_bf16_f32 v0, v4, v0
	v_cvt_pk_bf16_f32 v1, v1, v2
	v_cvt_pk_bf16_f32 v2, v8, v5
	v_cvt_pk_bf16_f32 v3, v6, v3
	ds_bpermute_b32 v224, v228, v0
	ds_bpermute_b32 v225, v228, v1
	ds_bpermute_b32 v226, v228, v2
	ds_bpermute_b32 v227, v228, v3
	s_waitcnt lgkmcnt(4)
	global_store_dwordx4 v[16:17], v[220:223], off
	s_waitcnt lgkmcnt(0)
	global_store_dwordx4 v[16:17], v[224:227], off offset:256
	s_setprio 0
	s_cbranch_vccnz .LBB0_1144
	s_andn2_b64 vcc, exec, s[0:1]
	s_cbranch_vccnz .LBB0_1143
	s_setprio 1
	s_barrier
	s_branch .LBB0_1143
